# v53 + split priority in the up GEMM + M0 save/restore stripped (stack of the two neutral-or-better changes)
# baseline (speedup 1.0000x reference)
; __device__ __forceinline__ int mk_lane() { int l; asm volatile("v_mbcnt_lo_u32_b32 %0, -1, 0\n\tv_mbcnt_hi_u32_b32 %0, -1, %0" : "=v"(l)); return l; }
; #define PG8_STAGE(bufoff, gbase, voff) do { _Pragma("unroll") for (int _i = 0; _i < 2; ++_i) glds16_s((gbase), (voff)[_i], ldsb + (unsigned)((bufoff) + _i * 8192)); } while (0)
; #define PG8_WAIT_V(n) asm volatile("s_waitcnt vmcnt(" #n ")" ::: "memory")
; template <class Prob, class Epi, bool I8 = false, bool ALIGN_EPI = true, bool SP2 = true>
; __device__ __forceinline__ void gemm_phase(LAS unsigned char* lds, int wave, const Prob& P, const Epi& E) {
;     const int tid_ = wave * 64 + mk_lane();
;     const int tid = tid_, wid = __builtin_amdgcn_readfirstlane(tid >> 6), lane = tid & 63, wr = wid >> 2, wc = wid & 3, fr = lane & 15, fq = lane >> 4;
;     const int K = P.K, nt = K / BK;
;     unsigned voffA[2], voffB[2];
; #pragma unroll
;     for (int i = 0; i < 2; ++i) { int R, C; stage_rc(tid * 16 + i * 8192, R, C); const int Rb = (R & ~31) + perm32(R & 31);
;         voffA[i] = P.a_rowoff(R) + (unsigned)C * 2u; voffB[i] = P.b_rowoff(Rb) + (unsigned)C * 2u; }
;     const size_t kstep = (size_t)(BK * 2);
;     const size_t hstepA = P.a_hstep(), hstepB = P.b_hstep();
;     const unsigned ldsw = (unsigned)wid * 1024u;
;     const unsigned ldsb = (unsigned)(size_t)lds + ldsw;
;     const int aoff = lds_byte(wr * 64 + fr, fq * 8), boff = lds_byte(wc * 32 + fr, fq * 8);
;     ...
;     Unit cur, nxt; int ui = 0;
;     if (!P.next(0, cur)) return;
;     Acc acc;
; #pragma unroll
;     for (int a = 0; a < 2; ++a)
; #pragma unroll
;         for (int b = 0; b < 2; ++b)
; #pragma unroll
;             for (int m = 0; m < 4; ++m)
; #pragma unroll
;                 for (int n = 0; n < 2; ++n) acc[a][b][m][n] = (f32x4){0.f, 0.f, 0.f, 0.f};
;     h16x8 At[4][2], B0[2][2], B1[2][2];
;     const char* cA = P.a_tile(cur); const char* cB = P.b_tile(cur);
;     if constexpr (SP2) {
;         PG8_STAGE(PG8_SB(0, 0), cB, voffB); PG8_STAGE(PG8_SB(0, 1), cB + hstepB, voffB); PG8_STAGE(PG8_SA(0, 0), cA, voffA); PG8_STAGE(PG8_SA(0, 1), cA + hstepA, voffA);
;         if (wr == 1) PG8_BAR;
;         PG8_WAIT_V(2); PG8_BAR;
;         PG8_STAGE(PG8_SB(1, 0), cB + kstep, voffB); PG8_STAGE(PG8_SA(1, 0), cA + kstep, voffA); PG8_STAGE(PG8_SB(1, 1), cB + hstepB + kstep, voffB);
;         PG8_WAIT_V(6); PG8_BAR;
.LBB0_1056:
	v_readlane_b32 s0, v254, 42
	v_readlane_b32 s4, v252, 23
	s_waitcnt lgkmcnt(0)
	s_barrier
	s_add_u32 s14, s30, 0x2d200000
	v_mbcnt_lo_u32_b32 v0, -1, 0
	v_mbcnt_hi_u32_b32 v0, -1, v0
	v_readlane_b32 s5, v252, 24
	v_add_u32_e32 v1, s0, v0
	s_addc_u32 s15, s31, 0
	v_readfirstlane_b32 s0, v1
	s_and_b64 vcc, exec, s[4:5]
	s_cbranch_vccz .LBB0_1088
	v_ashrrev_i32_e32 v3, 31, v1
	v_lshrrev_b32_e32 v3, 26, v3
	v_lshlrev_b32_e32 v2, 4, v1
	v_add_u32_e32 v3, v1, v3
	v_bfe_i32 v1, v1, 27, 1
	v_lshrrev_b32_e32 v1, 22, v1
	v_add_u32_e32 v1, v2, v1
	v_and_b32_e32 v1, 0xfffffc00, v1
	v_sub_u32_e32 v1, v2, v1
	v_lshrrev_b32_e32 v4, 4, v1
	v_bitop3_b32 v1, v4, v1, 32 bitop3:0x6c
	v_ashrrev_i32_e32 v5, 31, v1
	v_ashrrev_i32_e32 v3, 6, v3
	v_lshrrev_b32_e32 v5, 26, v5
	v_lshlrev_b32_e32 v4, 3, v3
	v_add_u32_e32 v5, v1, v5
	v_and_b32_e32 v4, -16, v4
	v_ashrrev_i32_e32 v6, 6, v5
	v_add_u32_e32 v4, v6, v4
	v_and_b32_e32 v5, 0xc0, v5
	v_sub_u32_e32 v1, v1, v5
	v_lshlrev_b32_e32 v5, 1, v4
	v_lshrrev_b32_e32 v8, 2, v4
	v_and_b32_e32 v6, 3, v6
	s_mov_b32 s1, 0x1fffe0
	v_mov_b32_e32 v9, 1
	v_and_b32_e32 v7, 24, v5
	v_and_b32_e32 v8, 4, v8
	v_and_or_b32 v6, v4, s1, v6
	v_lshlrev_b32_e32 v3, 5, v3
	v_ashrrev_i16_sdwa v1, v9, sext(v1) dst_sel:DWORD dst_unused:UNUSED_PAD src0_sel:DWORD src1_sel:BYTE_0
	v_or3_b32 v6, v6, v8, v7
	v_lshlrev_b32_e32 v7, 3, v4
	v_and_b32_e32 v3, 32, v3
	v_bfe_i32 v1, v1, 0, 16
	v_and_b32_e32 v5, 0x1fff80, v5
	v_and_b32_e32 v7, 0x78, v7
	v_bfe_u32 v4, v4, 4, 2
	v_or3_b32 v4, v5, v7, v4
	v_add_lshl_u32 v1, v3, v1, 1
	v_lshl_add_u32 v250, v4, 11, v1
	v_lshl_add_u32 v217, v6, 11, v1
	v_add_u32_e32 v1, 0x2000, v2
	v_ashrrev_i32_e32 v2, 31, v1
	v_lshrrev_b32_e32 v2, 22, v2
	v_add_u32_e32 v2, v1, v2
	v_ashrrev_i32_e32 v2, 10, v2
	v_mul_i32_i24_e32 v3, 0x400, v2
	v_sub_u32_e32 v1, v1, v3
	v_lshrrev_b32_e32 v3, 4, v1
	v_bitop3_b32 v1, v3, v1, 32 bitop3:0x6c
	v_ashrrev_i32_e32 v4, 31, v1
	v_lshrrev_b32_e32 v4, 26, v4
	v_lshlrev_b32_e32 v3, 3, v2
	v_add_u32_e32 v4, v1, v4
	v_and_b32_e32 v3, -16, v3
	v_ashrrev_i32_e32 v5, 6, v4
	v_add_u32_e32 v3, v5, v3
	v_and_b32_e32 v5, 3, v5
	v_and_b32_e32 v4, 0xc0, v4
	v_and_or_b32 v5, v3, s1, v5
	s_ashr_i32 s1, s0, 6
	v_sub_u32_e32 v1, v1, v4
	s_lshl_b32 s2, s1, 10
	s_ashr_i32 s64, s0, 8
	v_lshlrev_b32_e32 v2, 5, v2
	v_ashrrev_i16_sdwa v1, v9, sext(v1) dst_sel:DWORD dst_unused:UNUSED_PAD src0_sel:DWORD src1_sel:BYTE_0
	v_lshlrev_b32_e32 v4, 1, v3
	v_lshrrev_b32_e32 v7, 2, v3
	s_add_i32 s72, s2, 0
	v_readlane_b32 s4, v252, 48
	v_and_b32_e32 v2, 32, v2
	v_bfe_i32 v1, v1, 0, 16
	v_and_b32_e32 v6, 24, v4
	v_and_b32_e32 v7, 4, v7
	v_readlane_b32 s5, v252, 49
	s_add_u32 s44, s79, s4
	v_or3_b32 v5, v5, v7, v6
	v_add_lshl_u32 v1, v2, v1, 1
	s_addc_u32 s45, s40, s5
	s_add_i32 s73, s72, 0x10000
	s_mov_b32 m0, s73
	s_nop 0
	global_load_lds_dwordx4 v217, s[44:45]
	s_add_i32 s74, s72, 0x12000
	v_lshl_add_u32 v248, v5, 11, v1
	s_mov_b32 m0, s74
	s_nop 0
	global_load_lds_dwordx4 v248, s[44:45]
	s_add_u32 s4, s44, 0x40000
	s_addc_u32 s5, s45, 0
	s_add_i32 s75, s72, 0x14000
	s_mov_b32 m0, s75
	s_nop 0
	global_load_lds_dwordx4 v217, s[4:5]
	v_lshlrev_b32_e32 v6, 3, v3
	s_add_i32 s80, s72, 0x16000
	s_mov_b32 m0, s80
	s_nop 0
	global_load_lds_dwordx4 v248, s[4:5]
	v_readlane_b32 s4, v252, 56
	v_and_b32_e32 v4, 0x1fff80, v4
	v_and_b32_e32 v6, 0x78, v6
	v_bfe_u32 v3, v3, 4, 2
	v_readlane_b32 s5, v252, 57
	s_add_u32 s60, s41, s4
	v_or3_b32 v3, v4, v6, v3
	s_addc_u32 s61, s19, s5
	s_mov_b32 m0, s72
	s_nop 0
	global_load_lds_dwordx4 v250, s[60:61]
	s_add_i32 s81, s72, 0x2000
	v_lshl_add_u32 v247, v3, 11, v1
	s_mov_b32 m0, s81
	s_nop 0
	global_load_lds_dwordx4 v247, s[60:61]
	s_add_u32 s4, s60, 0x2000
	s_addc_u32 s5, s61, 0
	s_add_i32 s82, s72, 0x4000
	s_mov_b32 m0, s82
	s_nop 0
	global_load_lds_dwordx4 v250, s[4:5]
	s_add_i32 s83, s72, 0x6000
	s_mov_b32 m0, s83
	s_nop 0
	global_load_lds_dwordx4 v247, s[4:5]
	s_cmp_eq_u32 s64, 1
	s_cselect_b64 s[16:17], -1, 0
	s_setprio 0
	s_cmp_lg_u32 s64, 1
	s_cbranch_scc1 .LBB0_1059
	s_barrier
	s_setprio 1
